# prologue: weight-transpose phase0b runs before wait_mod+phase1 (hides the wait for the adaLN GEMV items); blocks unchanged, branches retargeted
# speedup vs baseline: 1.0011x; 1.0011x over previous
; DI int tid_() { int t = threadIdx.x; asm volatile("" : "+v"(t)); return t; }
; DI void phase0b(const Params& p, char* smem) {
;   const int t = tid_();
;   const int nT = p.n_ttiles;
;   __syncthreads();
;   const int G = gridDim.x;
;   int u = blockIdx.x;
;   float vn[8];
;   TTile tn_ = ttile_decode(p, u < nT ? u : 0);
;   if (u < nT) ttile_load(tn_, t, vn);
; __global__ void __launch_bounds__(NTH, 2) mega_kernel(Params p) {
;     ...
;   phase0a(p, smem);
;   wait_mod(p);
;   phase1(p);
;   phase0b(p, smem);
;   grid.sync();
.LBB0_117:
	s_or_b64 exec, exec, s[12:13]
	s_branch .LBB0_188
.Lp0b_entry:
	s_load_dword s42, s[0:1], 0x488
	v_mov_b32_e32 v14, v220
	s_mov_b32 s8, 0
	s_mov_b32 s9, 1
	s_waitcnt lgkmcnt(0)
	s_cmp_lt_i32 s2, s42
	s_cselect_b64 s[4:5], -1, 0
	s_and_b64 s[6:7], s[4:5], exec
	s_cselect_b32 s16, s2, 0
	s_add_u32 s20, s0, 0x1f0
	s_addc_u32 s21, s1, 0
	s_mov_b64 s[6:7], s[20:21]
	s_barrier
